# P7: prompt-first workgroups (blockIdx bit 3 clear) now run conv items before their sample units (orders: prompt-conv-samples / conv-prompt-samples) on top of p7a
# speedup vs baseline: 1.0013x; 1.0004x over previous
; __device__ __forceinline__ void mixer_phase(Frame& F, const Args& A) {
;     ...
;     for (int u = F.vcu; u < 256 * (PROBE_P7 == 1 ? 2 : 1); u += F.G) prompt_unit(F, A, (u & 255) >> 2, u & 3);
;     for (int u = F.vcu; u < 512 * (PROBE_P7 == 2 ? 2 : 1); u += F.G) sample_unit(F, A, (u & 511) >> 2, u & 3);
;     for (int u = F.vcu * NWAVES + F.wave; u < (M / 8) * 8 * (PROBE_P7 == 3 ? 2 : 1); u += F.G * NWAVES) conv_item(F, A, u % ((M / 8) * 8));
.LBB0_627:
	s_cmpk_eq_i32 s33, 0x100
	s_cbranch_scc0 .Lp7e_go
	s_bitcmp1_b32 s50, 3
	s_cbranch_scc1 .Lp7e_go
	s_cmp_eq_u32 s101, 14
	s_cbranch_scc1 .Lp7e_go
	v_writelane_b32 v253, s2, 32
	v_writelane_b32 v253, s3, 33
	v_writelane_b32 v253, s17, 34
	v_writelane_b32 v253, s18, 35
	v_writelane_b32 v253, s19, 36
	v_writelane_b32 v253, s20, 37
	v_writelane_b32 v253, s21, 38
	v_writelane_b32 v253, s22, 39
	v_writelane_b32 v253, s23, 40
	v_writelane_b32 v253, s46, 41
	v_writelane_b32 v253, s48, 42
	v_writelane_b32 v253, s54, 43
	v_writelane_b32 v253, s58, 44
	v_writelane_b32 v253, s59, 45
	v_writelane_b32 v253, s60, 46
	v_writelane_b32 v253, s61, 47
	v_writelane_b32 v253, s62, 48
	v_writelane_b32 v253, s63, 49
	v_writelane_b32 v253, s66, 50
	v_writelane_b32 v253, s67, 51
	v_writelane_b32 v253, s71, 52
	v_writelane_b32 v253, s88, 53
	v_writelane_b32 v253, s94, 54
	v_writelane_b32 v253, s95, 55
	v_writelane_b32 v253, s96, 56
	v_writelane_b32 v253, s97, 57
	s_mov_b32 s101, 13
	s_mov_b64 s[36:37], s[96:97]
	s_mov_b64 s[38:39], s[58:59]
	s_mov_b64 s[44:45], s[94:95]
	s_branch .LBB0_641

; __device__ __forceinline__ void mixer_phase(Frame& F, const Args& A) {
;     ...
;     for (int u = F.vcu; u < 256 * (PROBE_P7 == 1 ? 2 : 1); u += F.G) prompt_unit(F, A, (u & 255) >> 2, u & 3);
;     for (int u = F.vcu; u < 512 * (PROBE_P7 == 2 ? 2 : 1); u += F.G) sample_unit(F, A, (u & 511) >> 2, u & 3);
;     for (int u = F.vcu * NWAVES + F.wave; u < (M / 8) * 8 * (PROBE_P7 == 3 ? 2 : 1); u += F.G * NWAVES) conv_item(F, A, u % ((M / 8) * 8));
.LBB0_641:
	s_cmp_eq_u32 s101, 14
	s_cbranch_scc1 .Lp7e_skip
	s_cmp_eq_u32 s101, 7
	s_cbranch_scc0 .Lp7_doconv
.Lp7e_skip:
	s_mov_b64 s[96:97], s[36:37]
	s_mov_b64 s[58:59], s[38:39]
	s_mov_b64 s[94:95], s[44:45]
	s_mov_b32 s101, 0
	s_branch .LBB0_659

; __device__ __forceinline__ void mixer_phase(Frame& F, const Args& A) {
;     ...
;     for (int u = F.vcu; u < 256 * (PROBE_P7 == 1 ? 2 : 1); u += F.G) prompt_unit(F, A, (u & 255) >> 2, u & 3);
;     for (int u = F.vcu; u < 512 * (PROBE_P7 == 2 ? 2 : 1); u += F.G) sample_unit(F, A, (u & 511) >> 2, u & 3);
;     for (int u = F.vcu * NWAVES + F.wave; u < (M / 8) * 8 * (PROBE_P7 == 3 ? 2 : 1); u += F.G * NWAVES) conv_item(F, A, u % ((M / 8) * 8));
.LBB0_658:
	s_mov_b64 s[94:95], s[44:45]
	s_cmp_eq_u32 s101, 13
	s_cbranch_scc0 .Lp7e_not13
	s_mov_b32 s101, 14
	v_readlane_b32 s2, v253, 32
	v_readlane_b32 s3, v253, 33
	v_readlane_b32 s17, v253, 34
	v_readlane_b32 s18, v253, 35
	v_readlane_b32 s19, v253, 36
	v_readlane_b32 s20, v253, 37
	v_readlane_b32 s21, v253, 38
	v_readlane_b32 s22, v253, 39
	v_readlane_b32 s23, v253, 40
	v_readlane_b32 s46, v253, 41
	v_readlane_b32 s48, v253, 42
	v_readlane_b32 s54, v253, 43
	v_readlane_b32 s58, v253, 44
	v_readlane_b32 s59, v253, 45
	v_readlane_b32 s60, v253, 46
	v_readlane_b32 s61, v253, 47
	v_readlane_b32 s62, v253, 48
	v_readlane_b32 s63, v253, 49
	v_readlane_b32 s66, v253, 50
	v_readlane_b32 s67, v253, 51
	v_readlane_b32 s71, v253, 52
	v_readlane_b32 s88, v253, 53
	v_readlane_b32 s94, v253, 54
	v_readlane_b32 s95, v253, 55
	v_readlane_b32 s96, v253, 56
	v_readlane_b32 s97, v253, 57
	s_nop 7
	s_branch .LBB0_627
.Lp7e_not13:
	s_cmp_eq_u32 s101, 6
	s_cbranch_scc0 .LBB0_659
	s_mov_b32 s101, 7
	v_readlane_b32 s17, v253, 0
	v_readlane_b32 s18, v253, 1
	v_readlane_b32 s19, v253, 2
	v_readlane_b32 s20, v253, 3
	v_readlane_b32 s21, v253, 4
	v_readlane_b32 s22, v253, 5
	v_readlane_b32 s23, v253, 6
	v_readlane_b32 s48, v253, 7
	v_readlane_b32 s54, v253, 8
	v_readlane_b32 s58, v253, 9
	v_readlane_b32 s59, v253, 10
	v_readlane_b32 s60, v253, 11
	v_readlane_b32 s61, v253, 12
	v_readlane_b32 s62, v253, 13
	v_readlane_b32 s63, v253, 14
	v_readlane_b32 s66, v253, 15
	v_readlane_b32 s67, v253, 16
	v_readlane_b32 s88, v253, 17
	v_readlane_b32 s94, v253, 18
	v_readlane_b32 s95, v253, 19
	v_readlane_b32 s96, v253, 20
	v_readlane_b32 s97, v253, 21
	v_mov_b32_e32 v14, v223
	v_mov_b32_e32 v15, v224
	v_mov_b32_e32 v16, v225
	v_mov_b32_e32 v17, v226
	v_mov_b32_e32 v18, v227
	v_mov_b32_e32 v19, v228
	v_mov_b32_e32 v20, v229
	v_mov_b32_e32 v21, v230
	v_mov_b32_e32 v25, v231
	s_nop 7
	s_branch .Lp7_again
